# combination + F1 epilogue activation stores addressed by a scalar base per store and one 32-bit lane offset (no per-store v_mad_i64 / v_lshl_add_u64)
# baseline (speedup 1.0000x reference)
; __device__ __forceinline__ unsigned cvt_pk_bf16(float lo, float hi) { unsigned r; asm volatile("v_cvt_pk_bf16_f32 %0, %1, %2" : "=v"(r) : "v"(lo), "v"(hi)); return r; }
; #define EPI_ST16(p, v) __builtin_nontemporal_store((v), (u32x4*)(p))
; template <int SH> __device__ __forceinline__ float dpp_shr_fill(float fill, float cur) { return i2f(__builtin_amdgcn_update_dpp(f2i(fill), f2i(cur), 0x110 + SH, 0xf, 0xf, false)); }
; #define ACT(t) (!SK || KBASE(t) <= qlo + QBLK - 1)
;     __device__ __forceinline__ void operator()(f32x4 (&acc)[2][2][4][2], const Unit& u, int p, int wr, int wc, int fr, int fq) const {
;     ...
;                     const f32x4 x0 = acc[ai][bj][0][n], x1 = acc[ai][bj][1][n], x2 = acc[ai][bj][2][n], x3 = acc[ai][bj][3][n];
;                     f32x4 s2, s3;
; #pragma unroll
;                     for (int e = 0; e < 4; ++e) { s3[e] = dpp_shr_fill<1>(h63[e], x3[e]); s2[e] = dpp_shr_fill<1>(h62[e], x2[e]); }
;                     f32x4 r0 = bb + w2 * x0 + w1 * s3 + w0 * s2, r1 = bb + w2 * x1 + w1 * x0 + w0 * s3, r2 = bb + w2 * x2 + w1 * x1 + w0 * x0, r3 = bb + w2 * x3 + w1 * x2 + w0 * x1;
;                     asm volatile("" : "+v"(r0), "+v"(r1), "+v"(r2), "+v"(r3));
;                     acc[ai][bj][0][n] = r0; acc[ai][bj][1][n] = r1; acc[ai][bj][2][n] = r2; acc[ai][bj][3][n] = r3;
;                     __builtin_amdgcn_sched_barrier(0); }
; #pragma unroll
;             for (int m = 0; m < 4; ++m) { f32x4 o[2];
; #pragma unroll
;                 for (int n = 0; n < 2; ++n) { const f32x4 gt = acc[ai][0][m][n], a = gt * -1.4426950408889634f, gu = gt * acc[ai][1][m][n];
;                     f32x4 ex; ex.x = __builtin_amdgcn_exp2f(a.x); ex.y = __builtin_amdgcn_exp2f(a.y); ex.z = __builtin_amdgcn_exp2f(a.z); ex.w = __builtin_amdgcn_exp2f(a.w);
;                     const f32x4 d = ex + 1.0f; f32x4 r; r.x = __builtin_amdgcn_rcpf(d.x); r.y = __builtin_amdgcn_rcpf(d.y); r.z = __builtin_amdgcn_rcpf(d.z); r.w = __builtin_amdgcn_rcpf(d.w);
;                     o[n] = gu * r; }
;                 u32x4 w; w.x = cvt_pk_bf16(o[0][0], o[0][1]); w.y = cvt_pk_bf16(o[0][2], o[0][3]); w.z = cvt_pk_bf16(o[1][0], o[1][1]); w.w = cvt_pk_bf16(o[1][2], o[1][3]);
;                 EPI_ST16(ACT + (size_t)(row0 + ai * HALF + m) * 5504 + ch0, w); }
.LBB0_1343:
	s_waitcnt lgkmcnt(0)
	s_nop 0
	v_mov_b32_dpp v170, v118 row_shr:1 row_mask:0xf bank_mask:0xf
	v_mov_b32_dpp v171, v119 row_shr:1 row_mask:0xf bank_mask:0xf
	v_mov_b32_dpp v172, v120 row_shr:1 row_mask:0xf bank_mask:0xf
	v_mov_b32_dpp v173, v121 row_shr:1 row_mask:0xf bank_mask:0xf
	v_pk_fma_f32 v[176:177], v[104:105], v[156:157], v[168:169]
	v_pk_fma_f32 v[178:179], v[102:103], v[154:155], v[166:167]
	v_mov_b32_dpp v158, v122 row_shr:1 row_mask:0xf bank_mask:0xf
	v_mov_b32_dpp v159, v123 row_shr:1 row_mask:0xf bank_mask:0xf
	v_mov_b32_dpp v160, v124 row_shr:1 row_mask:0xf bank_mask:0xf
	v_mov_b32_dpp v161, v125 row_shr:1 row_mask:0xf bank_mask:0xf
	v_pk_fma_f32 v[178:179], v[150:151], v[170:171], v[178:179]
	v_pk_fma_f32 v[176:177], v[152:153], v[172:173], v[176:177]
	v_pk_fma_f32 v[158:159], v[130:131], v[158:159], v[178:179]
	v_pk_fma_f32 v[160:161], v[132:133], v[160:161], v[176:177]
	v_pk_fma_f32 v[176:177], v[100:101], v[156:157], v[168:169]
	v_pk_fma_f32 v[178:179], v[98:99], v[154:155], v[166:167]
	v_pk_fma_f32 v[176:177], v[104:105], v[152:153], v[176:177]
	v_pk_fma_f32 v[178:179], v[102:103], v[150:151], v[178:179]
	v_pk_fma_f32 v[172:173], v[132:133], v[172:173], v[176:177]
	v_pk_fma_f32 v[170:171], v[130:131], v[170:171], v[178:179]
	v_pk_fma_f32 v[176:177], v[124:125], v[156:157], v[168:169]
	v_pk_fma_f32 v[178:179], v[122:123], v[154:155], v[166:167]
	v_pk_fma_f32 v[120:121], v[120:121], v[156:157], v[168:169]
	v_pk_fma_f32 v[118:119], v[118:119], v[154:155], v[166:167]
	v_pk_fma_f32 v[176:177], v[100:101], v[152:153], v[176:177]
	v_pk_fma_f32 v[178:179], v[98:99], v[150:151], v[178:179]
	v_pk_fma_f32 v[120:121], v[124:125], v[152:153], v[120:121]
	v_pk_fma_f32 v[118:119], v[122:123], v[150:151], v[118:119]
	v_lshl_add_u32 v174, s94, 8, v207
	v_pk_fma_f32 v[104:105], v[104:105], v[132:133], v[176:177]
	v_pk_fma_f32 v[102:103], v[102:103], v[130:131], v[178:179]
	v_pk_fma_f32 v[100:101], v[100:101], v[132:133], v[120:121]
	v_pk_fma_f32 v[98:99], v[98:99], v[130:131], v[118:119]
	s_nop 0
	v_pk_mul_f32 v[118:119], v[116:117], s[42:43] op_sel_hi:[1,0]
	v_pk_mul_f32 v[120:121], v[114:115], s[42:43] op_sel_hi:[1,0]
	v_exp_f32_e32 v118, v118
	v_exp_f32_e32 v120, v120
	v_exp_f32_e32 v119, v119
	v_exp_f32_e32 v121, v121
	v_pk_mul_f32 v[122:123], v[148:149], s[42:43] op_sel_hi:[1,0]
	v_pk_mul_f32 v[124:125], v[146:147], s[42:43] op_sel_hi:[1,0]
	v_pk_add_f32 v[118:119], v[118:119], 1.0 op_sel_hi:[1,0]
	v_pk_add_f32 v[120:121], v[120:121], 1.0 op_sel_hi:[1,0]
	v_rcp_f32_e32 v118, v118
	v_rcp_f32_e32 v120, v120
	v_rcp_f32_e32 v121, v121
	v_rcp_f32_e32 v119, v119
	v_exp_f32_e32 v124, v124
	v_exp_f32_e32 v122, v122
	v_exp_f32_e32 v123, v123
	v_exp_f32_e32 v125, v125
	v_pk_mul_f32 v[116:117], v[116:117], v[164:165]
	v_pk_mul_f32 v[114:115], v[114:115], v[162:163]
	v_pk_mul_f32 v[116:117], v[118:119], v[116:117]
	v_pk_mul_f32 v[114:115], v[120:121], v[114:115]
	v_pk_add_f32 v[118:119], v[122:123], 1.0 op_sel_hi:[1,0]
	v_pk_add_f32 v[120:121], v[124:125], 1.0 op_sel_hi:[1,0]
	v_rcp_f32_e32 v118, v118
	v_rcp_f32_e32 v120, v120
	v_rcp_f32_e32 v119, v119
	v_rcp_f32_e32 v121, v121
	v_pk_mul_f32 v[122:123], v[148:149], v[160:161]
	v_pk_mul_f32 v[124:125], v[146:147], v[158:159]
	v_pk_mul_f32 v[122:123], v[118:119], v[122:123]
	v_pk_mul_f32 v[120:121], v[120:121], v[124:125]
	v_cvt_pk_bf16_f32 v118, v114, v115
	v_cvt_pk_bf16_f32 v119, v116, v117
	v_mov_b64_e32 v[116:117], s[76:77]
	v_cvt_pk_bf16_f32 v120, v120, v121
	v_cvt_pk_bf16_f32 v121, v122, v123
	v_mul_lo_u32 v114, v174, s22
	v_lshl_add_u32 v114, v200, 1, v114
	s_mov_b64 s[100:101], s[76:77]
	global_store_dwordx4 v114, v[118:121], s[100:101]
	v_pk_mul_f32 v[122:123], v[144:145], s[42:43] op_sel_hi:[1,0]
	v_pk_mul_f32 v[124:125], v[142:143], s[42:43] op_sel_hi:[1,0]
	v_pk_mul_f32 v[118:119], v[108:109], s[42:43] op_sel_hi:[1,0]
	v_pk_mul_f32 v[120:121], v[106:107], s[42:43] op_sel_hi:[1,0]
	v_exp_f32_e32 v118, v118
	v_exp_f32_e32 v119, v119
	v_exp_f32_e32 v120, v120
	v_exp_f32_e32 v121, v121
	v_exp_f32_e32 v122, v122
	v_pk_add_f32 v[118:119], v[118:119], 1.0 op_sel_hi:[1,0]
	v_exp_f32_e32 v123, v123
	v_pk_add_f32 v[120:121], v[120:121], 1.0 op_sel_hi:[1,0]
	v_rcp_f32_e32 v118, v118
	v_rcp_f32_e32 v119, v119
	v_rcp_f32_e32 v120, v120
	v_rcp_f32_e32 v121, v121
; __device__ __forceinline__ unsigned cvt_pk_bf16(float lo, float hi) { unsigned r; asm volatile("v_cvt_pk_bf16_f32 %0, %1, %2" : "=v"(r) : "v"(lo), "v"(hi)); return r; }
; #define EPI_ST16(p, v) __builtin_nontemporal_store((v), (u32x4*)(p))
; #define ACT(t) (!SK || KBASE(t) <= qlo + QBLK - 1)
;     __device__ __forceinline__ void operator()(f32x4 (&acc)[2][2][4][2], const Unit& u, int p, int wr, int wc, int fr, int fq) const {
;     ...
;             for (int m = 0; m < 4; ++m) { f32x4 o[2];
; #pragma unroll
;                 for (int n = 0; n < 2; ++n) { const f32x4 gt = acc[ai][0][m][n], a = gt * -1.4426950408889634f, gu = gt * acc[ai][1][m][n];
;                     f32x4 ex; ex.x = __builtin_amdgcn_exp2f(a.x); ex.y = __builtin_amdgcn_exp2f(a.y); ex.z = __builtin_amdgcn_exp2f(a.z); ex.w = __builtin_amdgcn_exp2f(a.w);
;                     const f32x4 d = ex + 1.0f; f32x4 r; r.x = __builtin_amdgcn_rcpf(d.x); r.y = __builtin_amdgcn_rcpf(d.y); r.z = __builtin_amdgcn_rcpf(d.z); r.w = __builtin_amdgcn_rcpf(d.w);
;                     o[n] = gu * r; }
;                 u32x4 w; w.x = cvt_pk_bf16(o[0][0], o[0][1]); w.y = cvt_pk_bf16(o[0][2], o[0][3]); w.z = cvt_pk_bf16(o[1][0], o[1][1]); w.w = cvt_pk_bf16(o[1][2], o[1][3]);
;                 EPI_ST16(ACT + (size_t)(row0 + ai * HALF + m) * 5504 + ch0, w); }
	v_exp_f32_e32 v124, v124
	v_exp_f32_e32 v125, v125
	v_pk_mul_f32 v[108:109], v[108:109], v[140:141]
	v_pk_mul_f32 v[106:107], v[106:107], v[138:139]
	v_pk_mul_f32 v[108:109], v[118:119], v[108:109]
	v_pk_add_f32 v[118:119], v[122:123], 1.0 op_sel_hi:[1,0]
	v_pk_mul_f32 v[106:107], v[120:121], v[106:107]
	v_pk_add_f32 v[120:121], v[124:125], 1.0 op_sel_hi:[1,0]
	v_rcp_f32_e32 v118, v118
	v_rcp_f32_e32 v119, v119
	v_rcp_f32_e32 v120, v120
	v_rcp_f32_e32 v121, v121
	v_pk_mul_f32 v[122:123], v[144:145], v[172:173]
	v_pk_mul_f32 v[124:125], v[142:143], v[170:171]
	v_pk_mul_f32 v[118:119], v[118:119], v[122:123]
	v_pk_mul_f32 v[120:121], v[120:121], v[124:125]
	v_cvt_pk_bf16_f32 v106, v106, v107
	v_cvt_pk_bf16_f32 v107, v108, v109
	v_pk_mul_f32 v[102:103], v[110:111], v[102:103]
	v_cvt_pk_bf16_f32 v108, v120, v121
	v_cvt_pk_bf16_f32 v109, v118, v119
	s_mul_i32 s100, s22, 0x1
	s_add_u32 s100, s76, s100
	s_addc_u32 s101, s77, 0
	global_store_dwordx4 v114, v[106:109], s[100:101]
	v_pk_mul_f32 v[120:121], v[110:111], s[42:43] op_sel_hi:[1,0]
	v_pk_mul_f32 v[118:119], v[112:113], s[42:43] op_sel_hi:[1,0]
	v_pk_mul_f32 v[108:109], v[90:91], s[42:43] op_sel_hi:[1,0]
	v_pk_mul_f32 v[106:107], v[92:93], s[42:43] op_sel_hi:[1,0]
	v_exp_f32_e32 v108, v108
	v_exp_f32_e32 v109, v109
	v_exp_f32_e32 v106, v106
	v_exp_f32_e32 v107, v107
	v_exp_f32_e32 v120, v120
	v_pk_add_f32 v[108:109], v[108:109], 1.0 op_sel_hi:[1,0]
	v_exp_f32_e32 v121, v121
	v_rcp_f32_e32 v108, v108
	v_rcp_f32_e32 v109, v109
	v_pk_mul_f32 v[90:91], v[90:91], v[134:135]
	v_pk_add_f32 v[106:107], v[106:107], 1.0 op_sel_hi:[1,0]
	v_exp_f32_e32 v118, v118
	v_rcp_f32_e32 v106, v106
	v_rcp_f32_e32 v107, v107
	v_exp_f32_e32 v119, v119
	v_pk_mul_f32 v[90:91], v[108:109], v[90:91]
	v_pk_add_f32 v[108:109], v[120:121], 1.0 op_sel_hi:[1,0]
	v_pk_mul_f32 v[92:93], v[92:93], v[136:137]
	v_rcp_f32_e32 v108, v108
	v_rcp_f32_e32 v109, v109
	v_pk_mul_f32 v[92:93], v[106:107], v[92:93]
	v_pk_add_f32 v[106:107], v[118:119], 1.0 op_sel_hi:[1,0]
	v_cvt_pk_bf16_f32 v90, v90, v91
	v_pk_mul_f32 v[102:103], v[108:109], v[102:103]
	v_rcp_f32_e32 v106, v106
	v_rcp_f32_e32 v107, v107
	v_cvt_pk_bf16_f32 v91, v92, v93
	v_cvt_pk_bf16_f32 v92, v102, v103
	v_pk_mul_f32 v[104:105], v[112:113], v[104:105]
	v_pk_mul_f32 v[104:105], v[106:107], v[104:105]
	s_nop 0
	v_cvt_pk_bf16_f32 v93, v104, v105
	s_mul_i32 s100, s22, 0x2
	s_add_u32 s100, s76, s100
	s_addc_u32 s101, s77, 0
	global_store_dwordx4 v114, v[90:93], s[100:101]
	v_pk_mul_f32 v[102:103], v[96:97], s[42:43] op_sel_hi:[1,0]
	v_pk_mul_f32 v[104:105], v[94:95], s[42:43] op_sel_hi:[1,0]
	v_pk_mul_f32 v[90:91], v[88:89], s[42:43] op_sel_hi:[1,0]
	v_pk_mul_f32 v[92:93], v[86:87], s[42:43] op_sel_hi:[1,0]
	v_exp_f32_e32 v90, v90
	v_exp_f32_e32 v91, v91
	v_exp_f32_e32 v92, v92
	v_exp_f32_e32 v93, v93
	v_exp_f32_e32 v102, v102
	v_pk_add_f32 v[90:91], v[90:91], 1.0 op_sel_hi:[1,0]
	v_exp_f32_e32 v103, v103
	v_pk_add_f32 v[92:93], v[92:93], 1.0 op_sel_hi:[1,0]
	v_rcp_f32_e32 v90, v90
	v_rcp_f32_e32 v91, v91
	v_rcp_f32_e32 v92, v92
	v_rcp_f32_e32 v93, v93
	v_exp_f32_e32 v104, v104
	v_exp_f32_e32 v105, v105
	v_pk_mul_f32 v[88:89], v[88:89], v[128:129]
	v_pk_mul_f32 v[86:87], v[86:87], v[126:127]
	v_pk_mul_f32 v[88:89], v[90:91], v[88:89]
	v_pk_add_f32 v[90:91], v[102:103], 1.0 op_sel_hi:[1,0]
	v_pk_mul_f32 v[86:87], v[92:93], v[86:87]
	v_pk_add_f32 v[92:93], v[104:105], 1.0 op_sel_hi:[1,0]
	v_rcp_f32_e32 v90, v90
	v_rcp_f32_e32 v91, v91
	v_rcp_f32_e32 v92, v92
	v_rcp_f32_e32 v93, v93
	v_pk_mul_f32 v[96:97], v[96:97], v[100:101]
	v_pk_mul_f32 v[94:95], v[94:95], v[98:99]
	v_pk_mul_f32 v[90:91], v[90:91], v[96:97]
	v_pk_mul_f32 v[92:93], v[92:93], v[94:95]
	v_cvt_pk_bf16_f32 v86, v86, v87
	v_cvt_pk_bf16_f32 v87, v88, v89
	s_nop 0
	v_cvt_pk_bf16_f32 v88, v92, v93
	v_cvt_pk_bf16_f32 v89, v90, v91
	s_mul_i32 s100, s22, 0x3
	s_add_u32 s100, s76, s100
	s_addc_u32 s101, s77, 0
	global_store_dwordx4 v114, v[86:89], s[100:101]
	ds_read_b128 v[88:91], v220
	ds_read_b128 v[92:95], v220 offset:1024
	ds_read_b128 v[96:99], v220 offset:2048
	ds_read_b128 v[100:103], v220 offset:3072
	v_cndmask_b32_e64 v87, 0, 1, s[82:83]
	v_cmp_ne_u32_e64 s[12:13], 1, v87
	s_andn2_b64 vcc, exec, s[82:83]
	s_cbranch_vccnz .Lzd_4
	ds_read_b128 v[108:111], v210 offset:2048
	ds_read_b128 v[104:107], v210 offset:3072

; __device__ __forceinline__ unsigned cvt_pk_bf16(float lo, float hi) { unsigned r; asm volatile("v_cvt_pk_bf16_f32 %0, %1, %2" : "=v"(r) : "v"(lo), "v"(hi)); return r; }
; #define EPI_ST16(p, v) __builtin_nontemporal_store((v), (u32x4*)(p))
; template <int SH> __device__ __forceinline__ float dpp_shr_fill(float fill, float cur) { return i2f(__builtin_amdgcn_update_dpp(f2i(fill), f2i(cur), 0x110 + SH, 0xf, 0xf, false)); }
; #define ACT(t) (!SK || KBASE(t) <= qlo + QBLK - 1)
;     __device__ __forceinline__ void operator()(f32x4 (&acc)[2][2][4][2], const Unit& u, int p, int wr, int wc, int fr, int fq) const {
;     ...
;                     const f32x4 x0 = acc[ai][bj][0][n], x1 = acc[ai][bj][1][n], x2 = acc[ai][bj][2][n], x3 = acc[ai][bj][3][n];
;                     f32x4 s2, s3;
; #pragma unroll
;                     for (int e = 0; e < 4; ++e) { s3[e] = dpp_shr_fill<1>(h63[e], x3[e]); s2[e] = dpp_shr_fill<1>(h62[e], x2[e]); }
;                     f32x4 r0 = bb + w2 * x0 + w1 * s3 + w0 * s2, r1 = bb + w2 * x1 + w1 * x0 + w0 * s3, r2 = bb + w2 * x2 + w1 * x1 + w0 * x0, r3 = bb + w2 * x3 + w1 * x2 + w0 * x1;
;                     asm volatile("" : "+v"(r0), "+v"(r1), "+v"(r2), "+v"(r3));
;                     acc[ai][bj][0][n] = r0; acc[ai][bj][1][n] = r1; acc[ai][bj][2][n] = r2; acc[ai][bj][3][n] = r3;
;                     __builtin_amdgcn_sched_barrier(0); }
; #pragma unroll
;             for (int m = 0; m < 4; ++m) { f32x4 o[2];
; #pragma unroll
;                 for (int n = 0; n < 2; ++n) { const f32x4 gt = acc[ai][0][m][n], a = gt * -1.4426950408889634f, gu = gt * acc[ai][1][m][n];
;                     f32x4 ex; ex.x = __builtin_amdgcn_exp2f(a.x); ex.y = __builtin_amdgcn_exp2f(a.y); ex.z = __builtin_amdgcn_exp2f(a.z); ex.w = __builtin_amdgcn_exp2f(a.w);
;                     const f32x4 d = ex + 1.0f; f32x4 r; r.x = __builtin_amdgcn_rcpf(d.x); r.y = __builtin_amdgcn_rcpf(d.y); r.z = __builtin_amdgcn_rcpf(d.z); r.w = __builtin_amdgcn_rcpf(d.w);
;                     o[n] = gu * r; }
;                 u32x4 w; w.x = cvt_pk_bf16(o[0][0], o[0][1]); w.y = cvt_pk_bf16(o[0][2], o[0][3]); w.z = cvt_pk_bf16(o[1][0], o[1][1]); w.w = cvt_pk_bf16(o[1][2], o[1][3]);
;                 EPI_ST16(ACT + (size_t)(row0 + ai * HALF + m) * 5504 + ch0, w); }
.LBB0_1351:
	v_mov_b32_e32 v94, v116
	v_mov_b32_e32 v95, v116
	v_pk_fma_f32 v[8:9], v[8:9], v[94:95], v[40:41]
	v_pk_fma_f32 v[6:7], v[6:7], v[116:117], v[38:39]
	v_mov_b32_e32 v94, v112
	v_mov_b32_e32 v95, v112
	v_pk_fma_f32 v[4:5], v[4:5], v[94:95], v[40:41]
	v_pk_fma_f32 v[2:3], v[2:3], v[112:113], v[38:39]
	s_waitcnt lgkmcnt(0)
	v_mov_b32_dpp v90, v42 row_shr:1 row_mask:0xf bank_mask:0xf
	v_mov_b32_dpp v91, v43 row_shr:1 row_mask:0xf bank_mask:0xf
	v_mov_b32_dpp v92, v44 row_shr:1 row_mask:0xf bank_mask:0xf
	v_mov_b32_dpp v93, v45 row_shr:1 row_mask:0xf bank_mask:0xf
	v_pk_fma_f32 v[38:39], v[8:9], v[80:81], v[88:89]
	v_pk_fma_f32 v[40:41], v[6:7], v[78:79], v[86:87]
	v_mov_b32_dpp v58, v34 row_shr:1 row_mask:0xf bank_mask:0xf
	v_mov_b32_dpp v59, v35 row_shr:1 row_mask:0xf bank_mask:0xf
	v_mov_b32_dpp v60, v36 row_shr:1 row_mask:0xf bank_mask:0xf
	v_mov_b32_dpp v61, v37 row_shr:1 row_mask:0xf bank_mask:0xf
	v_pk_fma_f32 v[94:95], v[52:53], v[92:93], v[38:39]
	v_pk_fma_f32 v[38:39], v[50:51], v[90:91], v[40:41]
	v_pk_fma_f32 v[40:41], v[48:49], v[60:61], v[94:95]
	v_pk_fma_f32 v[38:39], v[46:47], v[58:59], v[38:39]
	v_pk_fma_f32 v[58:59], v[4:5], v[80:81], v[88:89]
	v_pk_fma_f32 v[60:61], v[2:3], v[78:79], v[86:87]
	v_pk_fma_f32 v[58:59], v[8:9], v[52:53], v[58:59]
	v_pk_fma_f32 v[94:95], v[6:7], v[50:51], v[60:61]
	v_pk_fma_f32 v[60:61], v[48:49], v[92:93], v[58:59]
	v_pk_fma_f32 v[58:59], v[46:47], v[90:91], v[94:95]
	v_pk_fma_f32 v[90:91], v[36:37], v[80:81], v[88:89]
	v_pk_fma_f32 v[92:93], v[34:35], v[78:79], v[86:87]
	v_pk_fma_f32 v[44:45], v[44:45], v[80:81], v[88:89]
	v_pk_fma_f32 v[42:43], v[42:43], v[78:79], v[86:87]
	v_pk_fma_f32 v[90:91], v[4:5], v[52:53], v[90:91]
	v_pk_fma_f32 v[92:93], v[2:3], v[50:51], v[92:93]
	v_pk_fma_f32 v[36:37], v[36:37], v[52:53], v[44:45]
	v_pk_fma_f32 v[34:35], v[34:35], v[50:51], v[42:43]
	v_pk_fma_f32 v[8:9], v[8:9], v[48:49], v[90:91]
	v_pk_fma_f32 v[6:7], v[6:7], v[46:47], v[92:93]
	v_pk_fma_f32 v[4:5], v[4:5], v[48:49], v[36:37]
	v_pk_fma_f32 v[2:3], v[2:3], v[46:47], v[34:35]
	s_nop 0
	v_pk_mul_f32 v[34:35], v[84:85], s[42:43] op_sel_hi:[1,0]
	v_pk_mul_f32 v[36:37], v[82:83], s[42:43] op_sel_hi:[1,0]
	v_exp_f32_e32 v34, v34
	v_exp_f32_e32 v36, v36
	v_exp_f32_e32 v35, v35
	v_exp_f32_e32 v37, v37
	v_pk_mul_f32 v[46:47], v[76:77], s[42:43] op_sel_hi:[1,0]
	v_pk_mul_f32 v[48:49], v[74:75], s[42:43] op_sel_hi:[1,0]
	v_pk_add_f32 v[34:35], v[34:35], 1.0 op_sel_hi:[1,0]
	v_pk_add_f32 v[36:37], v[36:37], 1.0 op_sel_hi:[1,0]
	v_rcp_f32_e32 v34, v34
	v_rcp_f32_e32 v36, v36
	v_rcp_f32_e32 v37, v37
	v_rcp_f32_e32 v35, v35
	v_exp_f32_e32 v48, v48
	v_exp_f32_e32 v46, v46
	v_exp_f32_e32 v47, v47
	v_exp_f32_e32 v49, v49
	v_pk_mul_f32 v[42:43], v[84:85], v[64:65]
	v_pk_mul_f32 v[44:45], v[82:83], v[62:63]
	v_pk_mul_f32 v[34:35], v[34:35], v[42:43]
	v_pk_mul_f32 v[36:37], v[36:37], v[44:45]
	v_pk_add_f32 v[42:43], v[46:47], 1.0 op_sel_hi:[1,0]
	v_pk_add_f32 v[44:45], v[48:49], 1.0 op_sel_hi:[1,0]
	v_rcp_f32_e32 v42, v42
	v_rcp_f32_e32 v44, v44
	v_rcp_f32_e32 v43, v43
	v_rcp_f32_e32 v45, v45
	v_pk_mul_f32 v[40:41], v[76:77], v[40:41]
	v_pk_mul_f32 v[38:39], v[74:75], v[38:39]
	v_pk_mul_f32 v[40:41], v[42:43], v[40:41]
	v_pk_mul_f32 v[38:39], v[44:45], v[38:39]
	v_cvt_pk_bf16_f32 v36, v36, v37
	v_cvt_pk_bf16_f32 v37, v34, v35
	v_mov_b64_e32 v[34:35], s[76:77]
	v_cvt_pk_bf16_f32 v38, v38, v39
	v_cvt_pk_bf16_f32 v39, v40, v41
	s_mul_i32 s100, s22, 0x80
	s_add_u32 s100, s76, s100
	s_addc_u32 s101, s77, 0
	global_store_dwordx4 v114, v[36:39], s[100:101]
	v_pk_mul_f32 v[44:45], v[68:69], s[42:43] op_sel_hi:[1,0]
	v_pk_mul_f32 v[46:47], v[66:67], s[42:43] op_sel_hi:[1,0]
	v_pk_mul_f32 v[36:37], v[72:73], s[42:43] op_sel_hi:[1,0]
	v_pk_mul_f32 v[38:39], v[70:71], s[42:43] op_sel_hi:[1,0]
	v_exp_f32_e32 v36, v36
	v_exp_f32_e32 v38, v38
	v_exp_f32_e32 v37, v37
	v_exp_f32_e32 v39, v39
	v_exp_f32_e32 v46, v46
	v_exp_f32_e32 v44, v44
	v_pk_add_f32 v[36:37], v[36:37], 1.0 op_sel_hi:[1,0]
; __device__ __forceinline__ unsigned cvt_pk_bf16(float lo, float hi) { unsigned r; asm volatile("v_cvt_pk_bf16_f32 %0, %1, %2" : "=v"(r) : "v"(lo), "v"(hi)); return r; }
; #define EPI_ST16(p, v) __builtin_nontemporal_store((v), (u32x4*)(p))
; #define ACT(t) (!SK || KBASE(t) <= qlo + QBLK - 1)
;     __device__ __forceinline__ void operator()(f32x4 (&acc)[2][2][4][2], const Unit& u, int p, int wr, int wc, int fr, int fq) const {
;     ...
;             for (int m = 0; m < 4; ++m) { f32x4 o[2];
; #pragma unroll
;                 for (int n = 0; n < 2; ++n) { const f32x4 gt = acc[ai][0][m][n], a = gt * -1.4426950408889634f, gu = gt * acc[ai][1][m][n];
;                     f32x4 ex; ex.x = __builtin_amdgcn_exp2f(a.x); ex.y = __builtin_amdgcn_exp2f(a.y); ex.z = __builtin_amdgcn_exp2f(a.z); ex.w = __builtin_amdgcn_exp2f(a.w);
;                     const f32x4 d = ex + 1.0f; f32x4 r; r.x = __builtin_amdgcn_rcpf(d.x); r.y = __builtin_amdgcn_rcpf(d.y); r.z = __builtin_amdgcn_rcpf(d.z); r.w = __builtin_amdgcn_rcpf(d.w);
;                     o[n] = gu * r; }
;                 u32x4 w; w.x = cvt_pk_bf16(o[0][0], o[0][1]); w.y = cvt_pk_bf16(o[0][2], o[0][3]); w.z = cvt_pk_bf16(o[1][0], o[1][1]); w.w = cvt_pk_bf16(o[1][2], o[1][3]);
;                 EPI_ST16(ACT + (size_t)(row0 + ai * HALF + m) * 5504 + ch0, w); }
	v_pk_add_f32 v[38:39], v[38:39], 1.0 op_sel_hi:[1,0]
	v_rcp_f32_e32 v36, v36
	v_rcp_f32_e32 v38, v38
	v_rcp_f32_e32 v39, v39
	v_rcp_f32_e32 v37, v37
	v_exp_f32_e32 v45, v45
	v_exp_f32_e32 v47, v47
	v_pk_mul_f32 v[40:41], v[72:73], v[56:57]
	v_pk_mul_f32 v[42:43], v[70:71], v[54:55]
	v_pk_mul_f32 v[40:41], v[36:37], v[40:41]
	v_pk_mul_f32 v[36:37], v[38:39], v[42:43]
	v_pk_add_f32 v[38:39], v[44:45], 1.0 op_sel_hi:[1,0]
	v_pk_add_f32 v[42:43], v[46:47], 1.0 op_sel_hi:[1,0]
	v_rcp_f32_e32 v38, v38
	v_rcp_f32_e32 v42, v42
	v_rcp_f32_e32 v39, v39
	v_rcp_f32_e32 v43, v43
	v_pk_mul_f32 v[44:45], v[68:69], v[60:61]
	v_pk_mul_f32 v[46:47], v[66:67], v[58:59]
	v_cvt_pk_bf16_f32 v36, v36, v37
	v_cvt_pk_bf16_f32 v37, v40, v41
	v_pk_mul_f32 v[44:45], v[38:39], v[44:45]
	v_pk_mul_f32 v[38:39], v[42:43], v[46:47]
	v_cvt_pk_bf16_f32 v38, v38, v39
	v_cvt_pk_bf16_f32 v39, v44, v45
	s_mul_i32 s100, s22, 0x81
	s_add_u32 s100, s76, s100
	s_addc_u32 s101, s77, 0
	global_store_dwordx4 v114, v[36:39], s[100:101]
	v_pk_mul_f32 v[16:17], v[32:33], v[16:17]
	v_pk_mul_f32 v[14:15], v[30:31], v[14:15]
	v_pk_mul_f32 v[36:37], v[32:33], s[42:43] op_sel_hi:[1,0]
	v_pk_mul_f32 v[38:39], v[30:31], s[42:43] op_sel_hi:[1,0]
	v_exp_f32_e32 v36, v36
	v_exp_f32_e32 v38, v38
	v_exp_f32_e32 v37, v37
	v_exp_f32_e32 v39, v39
	v_pk_mul_f32 v[8:9], v[24:25], v[8:9]
	v_pk_mul_f32 v[6:7], v[22:23], v[6:7]
	v_pk_add_f32 v[30:31], v[36:37], 1.0 op_sel_hi:[1,0]
	v_pk_add_f32 v[32:33], v[38:39], 1.0 op_sel_hi:[1,0]
	v_pk_mul_f32 v[36:37], v[24:25], s[42:43] op_sel_hi:[1,0]
	v_pk_mul_f32 v[38:39], v[22:23], s[42:43] op_sel_hi:[1,0]
	v_rcp_f32_e32 v32, v32
	v_rcp_f32_e32 v33, v33
	v_rcp_f32_e32 v30, v30
	v_rcp_f32_e32 v31, v31
	v_exp_f32_e32 v38, v38
	v_exp_f32_e32 v36, v36
	v_exp_f32_e32 v37, v37
	v_exp_f32_e32 v39, v39
	v_pk_mul_f32 v[16:17], v[30:31], v[16:17]
	v_pk_mul_f32 v[14:15], v[32:33], v[14:15]
	v_pk_add_f32 v[30:31], v[36:37], 1.0 op_sel_hi:[1,0]
	v_pk_add_f32 v[32:33], v[38:39], 1.0 op_sel_hi:[1,0]
	v_rcp_f32_e32 v30, v30
	v_rcp_f32_e32 v32, v32
	v_rcp_f32_e32 v31, v31
	v_rcp_f32_e32 v33, v33
	v_pk_mul_f32 v[12:13], v[28:29], v[12:13]
	v_pk_mul_f32 v[10:11], v[26:27], v[10:11]
	v_pk_mul_f32 v[22:23], v[30:31], v[8:9]
	v_pk_mul_f32 v[8:9], v[32:33], v[6:7]
	v_cvt_pk_bf16_f32 v6, v14, v15
	v_cvt_pk_bf16_f32 v7, v16, v17
	v_cvt_pk_bf16_f32 v8, v8, v9
	v_cvt_pk_bf16_f32 v9, v22, v23
	s_mul_i32 s100, s22, 0x82
	s_add_u32 s100, s76, s100
	s_addc_u32 s101, s77, 0
	global_store_dwordx4 v114, v[6:9], s[100:101]
	v_pk_mul_f32 v[14:15], v[20:21], s[42:43] op_sel_hi:[1,0]
	v_pk_mul_f32 v[16:17], v[18:19], s[42:43] op_sel_hi:[1,0]
	v_pk_mul_f32 v[6:7], v[28:29], s[42:43] op_sel_hi:[1,0]
	v_pk_mul_f32 v[8:9], v[26:27], s[42:43] op_sel_hi:[1,0]
	v_exp_f32_e32 v6, v6
	v_exp_f32_e32 v8, v8
	v_exp_f32_e32 v7, v7
	v_exp_f32_e32 v9, v9
	v_exp_f32_e32 v16, v16
	v_exp_f32_e32 v14, v14
	v_pk_add_f32 v[6:7], v[6:7], 1.0 op_sel_hi:[1,0]
	v_pk_add_f32 v[8:9], v[8:9], 1.0 op_sel_hi:[1,0]
	v_rcp_f32_e32 v6, v6
	v_rcp_f32_e32 v8, v8
	v_rcp_f32_e32 v9, v9
	v_rcp_f32_e32 v7, v7
	v_exp_f32_e32 v15, v15
	v_exp_f32_e32 v17, v17
	v_pk_mul_f32 v[8:9], v[8:9], v[10:11]
	v_pk_mul_f32 v[6:7], v[6:7], v[12:13]
	v_pk_add_f32 v[10:11], v[14:15], 1.0 op_sel_hi:[1,0]
	v_pk_add_f32 v[12:13], v[16:17], 1.0 op_sel_hi:[1,0]
	v_rcp_f32_e32 v10, v10
	v_rcp_f32_e32 v12, v12
	v_rcp_f32_e32 v11, v11
	v_rcp_f32_e32 v13, v13
	v_pk_mul_f32 v[4:5], v[20:21], v[4:5]
	v_pk_mul_f32 v[2:3], v[18:19], v[2:3]
	v_pk_mul_f32 v[10:11], v[10:11], v[4:5]
	v_pk_mul_f32 v[4:5], v[12:13], v[2:3]
	v_cvt_pk_bf16_f32 v2, v8, v9
	v_cvt_pk_bf16_f32 v3, v6, v7
	v_cvt_pk_bf16_f32 v4, v4, v5
	v_cvt_pk_bf16_f32 v5, v10, v11
	s_mul_i32 s100, s22, 0x83
	s_add_u32 s100, s76, s100
	s_addc_u32 s101, s77, 0
	global_store_dwordx4 v114, v[2:5], s[100:101]
	s_andn2_b64 vcc, exec, s[8:9]
	s_mov_b64 s[8:9], -1
	s_cbranch_vccnz .LBB0_1323
	s_andn2_b64 vcc, exec, s[68:69]
	s_and_b32 s0, s58, 1
	s_cbranch_vccz .LBB0_1356
	s_andn2_b64 vcc, exec, s[70:71]
	s_cbranch_vccz .LBB0_1357
